# gate-up steady loop: the 9 redundant s_nop 0 that hipcc places between an LDS-DMA block and the next block's m0 write are dropped (each block keeps its own nop after the m0 write)
# speedup vs baseline: 1.0125x; 1.0125x over previous
; #define PG8_STAGE(bufoff, gbase, voff) do { _Pragma("unroll") for (int _i = 0; _i < 2; ++_i) { \
;         const unsigned _m0 = ldsb + (unsigned)((bufoff) + _i * 8192); const char* _gb = (const char*)(gbase); \
;         asm volatile("s_mov_b32 m0, %0\n\ts_nop 0\n\tglobal_load_lds_dwordx4 %1, %2" :: "s"(_m0), "v"((voff)[_i]), "s"(_gb) : "m0", "memory"); } } while (0)
; #define PG8_LDA(dst, b, h) do { _Pragma("unroll") for (int m = 0; m < 4; ++m) _Pragma("unroll") for (int k = 0; k < 2; ++k) dst[m][k] = *(const LAS bf16x8*)(lds + PG8_SA(b, h) + aoff + m * 2048 + k * 1024); } while (0)
; #define PG8_LDB(dst, b, h) do { _Pragma("unroll") for (int n = 0; n < 2; ++n) _Pragma("unroll") for (int k = 0; k < 2; ++k) dst[n][k] = *(const LAS bf16x8*)(lds + PG8_SB(b, h) + boff + n * 2048 + k * 1024); } while (0)
; template <class Epi, bool ALIGN_EPI>
; __device__ __forceinline__ void gemm_phase(LAS unsigned char* lds, const Gemm g, const StaticOrder& S, const Epi& E) {
;     ...
;         for (int t = 0; t < nt; t += 2) {
;             const bool last = (t == nt - 2);
;             const char* a1 = cA + (size_t)(t + 1) * kstep;
;             const char* a2 = last ? nA : cA + (size_t)(t + 2) * kstep; const char* b2 = last ? nB : cB + (size_t)(t + 2) * kstep;
;             const char* a3 = a2 + kstep; const char* b3 = b2 + kstep;
;             PG8_LDB(B0, 0, 0); PG8_LDB(B1, 0, 1); PG8_SCHED; PG8_LDA(At, 0, 0); PG8_STAGE(PG8_SA(1, 1), a1 + hstepA, voffA);
;             PG8_WAIT_V(8); PG8_WAIT_L(0); PG8_BAR; PG8_MMA(0, 0, At, B0); PG8_MMA(0, 1, At, B1); PG8_BAR; PG8_SCHED;
;             PG8_LDA(At, 0, 1); PG8_STAGE(PG8_SB(0, 0), b2, voffB); PG8_STAGE(PG8_SB(0, 1), b2 + hstepB, voffB); PG8_STAGE(PG8_SA(0, 0), a2, voffA);
;             PG8_WAIT_V(8); PG8_WAIT_L(0); PG8_BAR; PG8_MMA(1, 0, At, B0); PG8_MMA(1, 1, At, B1); PG8_BAR; PG8_SCHED;
;             PG8_LDB(B0, 1, 0); PG8_LDB(B1, 1, 1); PG8_SCHED; PG8_LDA(At, 1, 0); PG8_STAGE(PG8_SA(0, 1), a2 + hstepA, voffA);
;             PG8_WAIT_V(8); PG8_WAIT_L(0); PG8_BAR; PG8_MMA(0, 0, At, B0); PG8_MMA(0, 1, At, B1); PG8_BAR; PG8_SCHED;
;             PG8_LDA(At, 1, 1); PG8_STAGE(PG8_SB(1, 0), b3, voffB); PG8_STAGE(PG8_SB(1, 1), b3 + hstepB, voffB); PG8_STAGE(PG8_SA(1, 0), a3, voffA);
;             PG8_WAIT_V(8); PG8_WAIT_L(0); PG8_BAR; PG8_MMA(1, 0, At, B0); PG8_MMA(1, 1, At, B1); PG8_BAR; PG8_SCHED;
.LBB0_306:
	v_add_u32_e32 v134, 0x10000, v185
	v_add_u32_e32 v158, 0x14000, v185
	ds_read_b128 v[74:77], v134
	ds_read_b128 v[94:97], v134 offset:1024
	ds_read_b128 v[114:117], v134 offset:2048
	ds_read_b128 v[134:137], v134 offset:3072
	ds_read_b128 v[146:149], v158
	ds_read_b128 v[150:153], v158 offset:1024
	ds_read_b128 v[154:157], v158 offset:2048
	ds_read_b128 v[158:161], v158 offset:3072
	s_add_u32 s30, s92, 0xfffc0080
	s_addc_u32 s31, s93, -1
	s_cmp_eq_u32 s50, 12
	s_cselect_b32 s60, s5, s30
	s_cselect_b32 s61, s4, s31
	s_cselect_b32 s58, s37, s41
	s_cselect_b32 s59, s35, s49
	s_add_u32 s56, s60, 0x80
	s_addc_u32 s57, s61, 0
	ds_read_b128 v[162:165], v186
	ds_read_b128 v[166:169], v186 offset:1024
	ds_read_b128 v[170:173], v186 offset:2048
	ds_read_b128 v[174:177], v186 offset:3072
	ds_read_b128 v[188:191], v186 offset:4096
	ds_read_b128 v[202:205], v186 offset:5120
	ds_read_b128 v[206:209], v186 offset:6144
	ds_read_b128 v[210:213], v186 offset:7168
	s_mov_b32 m0, s67
	s_nop 0
	global_load_lds_dwordx4 v0, s[92:93]
	s_mov_b32 m0, s65
	s_nop 0
	global_load_lds_dwordx4 v181, s[92:93]
	s_waitcnt vmcnt(8)
	s_waitcnt lgkmcnt(0)
	s_setprio 1
	s_barrier
	v_mfma_f32_16x16x32_bf16 v[142:145], v[74:77], v[162:165], v[142:145]
	v_mfma_f32_16x16x32_bf16 v[142:145], v[94:97], v[166:169], v[142:145]
	v_mfma_f32_16x16x32_bf16 v[138:141], v[114:117], v[162:165], v[138:141]
	v_mfma_f32_16x16x32_bf16 v[138:141], v[134:137], v[166:169], v[138:141]
	v_mfma_f32_16x16x32_bf16 v[130:133], v[146:149], v[162:165], v[130:133]
	v_mfma_f32_16x16x32_bf16 v[130:133], v[150:153], v[166:169], v[130:133]
	v_mfma_f32_16x16x32_bf16 v[126:129], v[154:157], v[162:165], v[126:129]
	v_mfma_f32_16x16x32_bf16 v[126:129], v[158:161], v[166:169], v[126:129]
	v_mfma_f32_16x16x32_bf16 v[106:109], v[154:157], v[170:173], v[106:109]
	v_mfma_f32_16x16x32_bf16 v[106:109], v[158:161], v[174:177], v[106:109]
	v_mfma_f32_16x16x32_bf16 v[110:113], v[146:149], v[170:173], v[110:113]
	v_mfma_f32_16x16x32_bf16 v[110:113], v[150:153], v[174:177], v[110:113]
	v_mfma_f32_16x16x32_bf16 v[118:121], v[114:117], v[170:173], v[118:121]
	v_mfma_f32_16x16x32_bf16 v[118:121], v[134:137], v[174:177], v[118:121]
	v_mfma_f32_16x16x32_bf16 v[122:125], v[74:77], v[170:173], v[122:125]
	v_mfma_f32_16x16x32_bf16 v[122:125], v[94:97], v[174:177], v[122:125]
	v_mfma_f32_16x16x32_bf16 v[102:105], v[74:77], v[188:191], v[102:105]
	v_mfma_f32_16x16x32_bf16 v[102:105], v[94:97], v[202:205], v[102:105]
	v_mfma_f32_16x16x32_bf16 v[98:101], v[114:117], v[188:191], v[98:101]
	v_mfma_f32_16x16x32_bf16 v[98:101], v[134:137], v[202:205], v[98:101]
	v_mfma_f32_16x16x32_bf16 v[90:93], v[146:149], v[188:191], v[90:93]
	v_mfma_f32_16x16x32_bf16 v[90:93], v[150:153], v[202:205], v[90:93]
	v_mfma_f32_16x16x32_bf16 v[86:89], v[154:157], v[188:191], v[86:89]
	v_mfma_f32_16x16x32_bf16 v[86:89], v[158:161], v[202:205], v[86:89]
	v_mfma_f32_16x16x32_bf16 v[66:69], v[154:157], v[206:209], v[66:69]
	v_mfma_f32_16x16x32_bf16 v[66:69], v[158:161], v[210:213], v[66:69]
	v_mfma_f32_16x16x32_bf16 v[70:73], v[146:149], v[206:209], v[70:73]
	v_mfma_f32_16x16x32_bf16 v[70:73], v[150:153], v[210:213], v[70:73]
	v_mfma_f32_16x16x32_bf16 v[78:81], v[114:117], v[206:209], v[78:81]
	v_mfma_f32_16x16x32_bf16 v[78:81], v[134:137], v[210:213], v[78:81]
	v_mfma_f32_16x16x32_bf16 v[82:85], v[74:77], v[206:209], v[82:85]
	v_mfma_f32_16x16x32_bf16 v[82:85], v[94:97], v[210:213], v[82:85]
	s_barrier
	s_setprio 0
	ds_read_b128 v[162:165], v186 offset:16384
	ds_read_b128 v[166:169], v186 offset:17408
	ds_read_b128 v[170:173], v186 offset:18432
	ds_read_b128 v[174:177], v186 offset:19456
	ds_read_b128 v[188:191], v186 offset:20480
	ds_read_b128 v[202:205], v186 offset:21504
	ds_read_b128 v[206:209], v186 offset:22528
	ds_read_b128 v[210:213], v186 offset:23552
	s_mov_b32 m0, s29
	s_nop 0
	global_load_lds_dwordx4 v180, s[58:59]
	s_add_u32 s30, s58, 0x40000
	s_mov_b32 m0, s42
	s_nop 0
	global_load_lds_dwordx4 v182, s[58:59]
	s_addc_u32 s31, s59, 0
	s_mov_b32 m0, s43
	s_nop 0
	global_load_lds_dwordx4 v180, s[30:31]
	s_mov_b32 m0, s44
	s_nop 0
	global_load_lds_dwordx4 v182, s[30:31]
	s_mov_b32 m0, s15
	s_nop 0
	global_load_lds_dwordx4 v0, s[60:61]
	s_mov_b32 m0, s45
	s_nop 0
	global_load_lds_dwordx4 v181, s[60:61]
	s_waitcnt vmcnt(8)
	s_waitcnt lgkmcnt(0)
	s_setprio 1
	s_barrier
	v_mfma_f32_16x16x32_bf16 v[62:65], v[74:77], v[162:165], v[62:65]
	v_mfma_f32_16x16x32_bf16 v[62:65], v[94:97], v[166:169], v[62:65]
	v_mfma_f32_16x16x32_bf16 v[58:61], v[114:117], v[162:165], v[58:61]
	v_mfma_f32_16x16x32_bf16 v[58:61], v[134:137], v[166:169], v[58:61]
	v_mfma_f32_16x16x32_bf16 v[54:57], v[146:149], v[162:165], v[54:57]
	v_mfma_f32_16x16x32_bf16 v[54:57], v[150:153], v[166:169], v[54:57]
	v_mfma_f32_16x16x32_bf16 v[50:53], v[154:157], v[162:165], v[50:53]
	v_mfma_f32_16x16x32_bf16 v[50:53], v[158:161], v[166:169], v[50:53]
	v_mfma_f32_16x16x32_bf16 v[34:37], v[154:157], v[170:173], v[34:37]
	v_mfma_f32_16x16x32_bf16 v[34:37], v[158:161], v[174:177], v[34:37]
	v_mfma_f32_16x16x32_bf16 v[38:41], v[146:149], v[170:173], v[38:41]
	v_mfma_f32_16x16x32_bf16 v[38:41], v[150:153], v[174:177], v[38:41]
	v_mfma_f32_16x16x32_bf16 v[42:45], v[114:117], v[170:173], v[42:45]
	v_mfma_f32_16x16x32_bf16 v[42:45], v[134:137], v[174:177], v[42:45]
	v_mfma_f32_16x16x32_bf16 v[46:49], v[74:77], v[170:173], v[46:49]
	v_mfma_f32_16x16x32_bf16 v[46:49], v[94:97], v[174:177], v[46:49]
	v_mfma_f32_16x16x32_bf16 v[30:33], v[74:77], v[188:191], v[30:33]
	v_mfma_f32_16x16x32_bf16 v[30:33], v[94:97], v[202:205], v[30:33]
	v_mfma_f32_16x16x32_bf16 v[26:29], v[114:117], v[188:191], v[26:29]
	v_mfma_f32_16x16x32_bf16 v[26:29], v[134:137], v[202:205], v[26:29]
	v_mfma_f32_16x16x32_bf16 v[22:25], v[146:149], v[188:191], v[22:25]
	v_mfma_f32_16x16x32_bf16 v[22:25], v[150:153], v[202:205], v[22:25]
	v_mfma_f32_16x16x32_bf16 v[18:21], v[154:157], v[188:191], v[18:21]
	v_mfma_f32_16x16x32_bf16 v[18:21], v[158:161], v[202:205], v[18:21]
	v_mfma_f32_16x16x32_bf16 v[2:5], v[154:157], v[206:209], v[2:5]
	v_mfma_f32_16x16x32_bf16 v[2:5], v[158:161], v[210:213], v[2:5]
	v_mfma_f32_16x16x32_bf16 v[6:9], v[146:149], v[206:209], v[6:9]
	v_mfma_f32_16x16x32_bf16 v[6:9], v[150:153], v[210:213], v[6:9]
	v_mfma_f32_16x16x32_bf16 v[10:13], v[114:117], v[206:209], v[10:13]
	v_mfma_f32_16x16x32_bf16 v[10:13], v[134:137], v[210:213], v[10:13]
	v_mfma_f32_16x16x32_bf16 v[14:17], v[74:77], v[206:209], v[14:17]
	v_mfma_f32_16x16x32_bf16 v[14:17], v[94:97], v[210:213], v[14:17]
	s_barrier
; #define PG8_STAGE(bufoff, gbase, voff) do { _Pragma("unroll") for (int _i = 0; _i < 2; ++_i) { \
;         const unsigned _m0 = ldsb + (unsigned)((bufoff) + _i * 8192); const char* _gb = (const char*)(gbase); \
;         asm volatile("s_mov_b32 m0, %0\n\ts_nop 0\n\tglobal_load_lds_dwordx4 %1, %2" :: "s"(_m0), "v"((voff)[_i]), "s"(_gb) : "m0", "memory"); } } while (0)
; #define PG8_LDA(dst, b, h) do { _Pragma("unroll") for (int m = 0; m < 4; ++m) _Pragma("unroll") for (int k = 0; k < 2; ++k) dst[m][k] = *(const LAS bf16x8*)(lds + PG8_SA(b, h) + aoff + m * 2048 + k * 1024); } while (0)
; #define PG8_LDB(dst, b, h) do { _Pragma("unroll") for (int n = 0; n < 2; ++n) _Pragma("unroll") for (int k = 0; k < 2; ++k) dst[n][k] = *(const LAS bf16x8*)(lds + PG8_SB(b, h) + boff + n * 2048 + k * 1024); } while (0)
; #define PG8_MMA(ai, bj, At, Bt) do { __builtin_amdgcn_s_setprio(1); _Pragma("unroll") for (int m = 0; m < 4; ++m) _Pragma("unroll") for (int n = 0; n < 2; ++n) _Pragma("unroll") for (int k = 0; k < 2; ++k) \
;         acc[ai][bj][m][n] = __builtin_amdgcn_mfma_f32_16x16x32_bf16(Bt[n][k], At[m][k], acc[ai][bj][m][n], 0, 0, 0); __builtin_amdgcn_s_setprio(0); } while (0)
; #define PG8_WAIT_V(n) asm volatile("s_waitcnt vmcnt(" #n ")" ::: "memory")
; #define PG8_WAIT_L(n) asm volatile("s_waitcnt lgkmcnt(" #n ")" ::: "memory")
; #define PG8_BAR __builtin_amdgcn_s_barrier()
; #define PG8_SCHED __builtin_amdgcn_sched_barrier(0)
; template <class Epi, bool ALIGN_EPI>
; __device__ __forceinline__ void gemm_phase(LAS unsigned char* lds, const Gemm g, const StaticOrder& S, const Epi& E) {
;     ...
;             PG8_LDB(B0, 1, 0); PG8_LDB(B1, 1, 1); PG8_SCHED; PG8_LDA(At, 1, 0); PG8_STAGE(PG8_SA(0, 1), a2 + hstepA, voffA);
;             PG8_WAIT_V(8); PG8_WAIT_L(0); PG8_BAR; PG8_MMA(0, 0, At, B0); PG8_MMA(0, 1, At, B1); PG8_BAR; PG8_SCHED;
;             PG8_LDA(At, 1, 1); PG8_STAGE(PG8_SB(1, 0), b3, voffB); PG8_STAGE(PG8_SB(1, 1), b3 + hstepB, voffB); PG8_STAGE(PG8_SA(1, 0), a3, voffA);
;             PG8_WAIT_V(8); PG8_WAIT_L(0); PG8_BAR; PG8_MMA(1, 0, At, B0); PG8_MMA(1, 1, At, B1); PG8_BAR; PG8_SCHED;
;         }
;         if constexpr (ALIGN_EPI) { if (wr == 0) PG8_BAR; }
	s_setprio 0
	v_add_u32_e32 v134, 0x18000, v185
	v_add_u32_e32 v158, 0x1c000, v185
	ds_read_b128 v[74:77], v134
	ds_read_b128 v[94:97], v134 offset:1024
	ds_read_b128 v[114:117], v134 offset:2048
	ds_read_b128 v[134:137], v134 offset:3072
	ds_read_b128 v[146:149], v158
	ds_read_b128 v[150:153], v158 offset:1024
	ds_read_b128 v[154:157], v158 offset:2048
	ds_read_b128 v[158:161], v158 offset:3072
	ds_read_b128 v[162:165], v186 offset:32768
	ds_read_b128 v[166:169], v186 offset:33792
	ds_read_b128 v[170:173], v186 offset:34816
	ds_read_b128 v[174:177], v186 offset:35840
	ds_read_b128 v[188:191], v186 offset:36864
	ds_read_b128 v[202:205], v186 offset:37888
	ds_read_b128 v[206:209], v186 offset:38912
	ds_read_b128 v[210:213], v186 offset:39936
	s_add_u32 s30, s60, 0x40000
	s_addc_u32 s31, s61, 0
	s_mov_b32 m0, s55
	s_nop 0
	global_load_lds_dwordx4 v0, s[30:31]
	s_mov_b32 m0, s88
	s_nop 0
	global_load_lds_dwordx4 v181, s[30:31]
	s_waitcnt vmcnt(8)
	s_waitcnt lgkmcnt(0)
	s_setprio 1
	s_barrier
	v_mfma_f32_16x16x32_bf16 v[142:145], v[74:77], v[162:165], v[142:145]
	v_mfma_f32_16x16x32_bf16 v[142:145], v[94:97], v[166:169], v[142:145]
	v_mfma_f32_16x16x32_bf16 v[138:141], v[114:117], v[162:165], v[138:141]
	v_mfma_f32_16x16x32_bf16 v[138:141], v[134:137], v[166:169], v[138:141]
	v_mfma_f32_16x16x32_bf16 v[130:133], v[146:149], v[162:165], v[130:133]
	v_mfma_f32_16x16x32_bf16 v[130:133], v[150:153], v[166:169], v[130:133]
	v_mfma_f32_16x16x32_bf16 v[126:129], v[154:157], v[162:165], v[126:129]
	v_mfma_f32_16x16x32_bf16 v[126:129], v[158:161], v[166:169], v[126:129]
	v_mfma_f32_16x16x32_bf16 v[106:109], v[154:157], v[170:173], v[106:109]
	v_mfma_f32_16x16x32_bf16 v[106:109], v[158:161], v[174:177], v[106:109]
	v_mfma_f32_16x16x32_bf16 v[110:113], v[146:149], v[170:173], v[110:113]
	v_mfma_f32_16x16x32_bf16 v[110:113], v[150:153], v[174:177], v[110:113]
	v_mfma_f32_16x16x32_bf16 v[118:121], v[114:117], v[170:173], v[118:121]
	v_mfma_f32_16x16x32_bf16 v[118:121], v[134:137], v[174:177], v[118:121]
	v_mfma_f32_16x16x32_bf16 v[122:125], v[74:77], v[170:173], v[122:125]
	v_mfma_f32_16x16x32_bf16 v[122:125], v[94:97], v[174:177], v[122:125]
	v_mfma_f32_16x16x32_bf16 v[102:105], v[74:77], v[188:191], v[102:105]
	v_mfma_f32_16x16x32_bf16 v[102:105], v[94:97], v[202:205], v[102:105]
	v_mfma_f32_16x16x32_bf16 v[98:101], v[114:117], v[188:191], v[98:101]
	v_mfma_f32_16x16x32_bf16 v[98:101], v[134:137], v[202:205], v[98:101]
	v_mfma_f32_16x16x32_bf16 v[90:93], v[146:149], v[188:191], v[90:93]
	v_mfma_f32_16x16x32_bf16 v[90:93], v[150:153], v[202:205], v[90:93]
	v_mfma_f32_16x16x32_bf16 v[86:89], v[154:157], v[188:191], v[86:89]
	v_mfma_f32_16x16x32_bf16 v[86:89], v[158:161], v[202:205], v[86:89]
	v_mfma_f32_16x16x32_bf16 v[66:69], v[154:157], v[206:209], v[66:69]
	v_mfma_f32_16x16x32_bf16 v[66:69], v[158:161], v[210:213], v[66:69]
	v_mfma_f32_16x16x32_bf16 v[70:73], v[146:149], v[206:209], v[70:73]
	v_mfma_f32_16x16x32_bf16 v[70:73], v[150:153], v[210:213], v[70:73]
	v_mfma_f32_16x16x32_bf16 v[78:81], v[114:117], v[206:209], v[78:81]
	v_mfma_f32_16x16x32_bf16 v[78:81], v[134:137], v[210:213], v[78:81]
	v_mfma_f32_16x16x32_bf16 v[82:85], v[74:77], v[206:209], v[82:85]
	v_mfma_f32_16x16x32_bf16 v[82:85], v[94:97], v[210:213], v[82:85]
	s_barrier
	s_setprio 0
	ds_read_b128 v[162:165], v186 offset:49152
	ds_read_b128 v[166:169], v186 offset:50176
	ds_read_b128 v[170:173], v186 offset:51200
	ds_read_b128 v[174:177], v186 offset:52224
	ds_read_b128 v[188:191], v186 offset:53248
	ds_read_b128 v[202:205], v186 offset:54272
	ds_read_b128 v[206:209], v186 offset:55296
	ds_read_b128 v[210:213], v186 offset:56320
	s_add_u32 s30, s58, 0x80
	s_addc_u32 s31, s59, 0
	s_mov_b32 m0, s94
	s_nop 0
	global_load_lds_dwordx4 v180, s[30:31]
	s_mov_b32 m0, s95
	s_nop 0
	global_load_lds_dwordx4 v182, s[30:31]
	s_add_u32 s30, s58, 0x40080
	s_addc_u32 s31, s59, 0
	s_mov_b32 m0, s17
	s_nop 0
	global_load_lds_dwordx4 v180, s[30:31]
	s_mov_b32 m0, s53
	s_nop 0
	global_load_lds_dwordx4 v182, s[30:31]
	s_mov_b32 m0, s96
	s_nop 0
	global_load_lds_dwordx4 v0, s[56:57]
	s_mov_b32 m0, s97
	s_nop 0
	global_load_lds_dwordx4 v181, s[56:57]
	s_waitcnt vmcnt(8)
	s_waitcnt lgkmcnt(0)
	s_setprio 1
	s_barrier
	v_mfma_f32_16x16x32_bf16 v[62:65], v[74:77], v[162:165], v[62:65]
	v_mfma_f32_16x16x32_bf16 v[62:65], v[94:97], v[166:169], v[62:65]
	v_mfma_f32_16x16x32_bf16 v[58:61], v[114:117], v[162:165], v[58:61]
	v_mfma_f32_16x16x32_bf16 v[58:61], v[134:137], v[166:169], v[58:61]
	v_mfma_f32_16x16x32_bf16 v[54:57], v[146:149], v[162:165], v[54:57]
	v_mfma_f32_16x16x32_bf16 v[54:57], v[150:153], v[166:169], v[54:57]
	v_mfma_f32_16x16x32_bf16 v[50:53], v[154:157], v[162:165], v[50:53]
	v_mfma_f32_16x16x32_bf16 v[50:53], v[158:161], v[166:169], v[50:53]
	v_mfma_f32_16x16x32_bf16 v[34:37], v[154:157], v[170:173], v[34:37]
	v_mfma_f32_16x16x32_bf16 v[34:37], v[158:161], v[174:177], v[34:37]
	v_mfma_f32_16x16x32_bf16 v[38:41], v[146:149], v[170:173], v[38:41]
	v_mfma_f32_16x16x32_bf16 v[38:41], v[150:153], v[174:177], v[38:41]
	v_mfma_f32_16x16x32_bf16 v[42:45], v[114:117], v[170:173], v[42:45]
	v_mfma_f32_16x16x32_bf16 v[42:45], v[134:137], v[174:177], v[42:45]
	v_mfma_f32_16x16x32_bf16 v[46:49], v[74:77], v[170:173], v[46:49]
	v_mfma_f32_16x16x32_bf16 v[46:49], v[94:97], v[174:177], v[46:49]
	v_mfma_f32_16x16x32_bf16 v[30:33], v[74:77], v[188:191], v[30:33]
	v_mfma_f32_16x16x32_bf16 v[30:33], v[94:97], v[202:205], v[30:33]
	v_mfma_f32_16x16x32_bf16 v[26:29], v[114:117], v[188:191], v[26:29]
	v_mfma_f32_16x16x32_bf16 v[26:29], v[134:137], v[202:205], v[26:29]
	v_mfma_f32_16x16x32_bf16 v[22:25], v[146:149], v[188:191], v[22:25]
	v_mfma_f32_16x16x32_bf16 v[22:25], v[150:153], v[202:205], v[22:25]
	v_mfma_f32_16x16x32_bf16 v[18:21], v[154:157], v[188:191], v[18:21]
	v_mfma_f32_16x16x32_bf16 v[18:21], v[158:161], v[202:205], v[18:21]
	v_mfma_f32_16x16x32_bf16 v[2:5], v[154:157], v[206:209], v[2:5]
	v_mfma_f32_16x16x32_bf16 v[2:5], v[158:161], v[210:213], v[2:5]
	v_mfma_f32_16x16x32_bf16 v[6:9], v[146:149], v[206:209], v[6:9]
	v_mfma_f32_16x16x32_bf16 v[6:9], v[150:153], v[210:213], v[6:9]
	v_mfma_f32_16x16x32_bf16 v[10:13], v[114:117], v[206:209], v[10:13]
	v_mfma_f32_16x16x32_bf16 v[10:13], v[134:137], v[210:213], v[10:13]
	v_mfma_f32_16x16x32_bf16 v[14:17], v[74:77], v[206:209], v[14:17]
	v_mfma_f32_16x16x32_bf16 v[14:17], v[94:97], v[210:213], v[14:17]
	s_barrier
	s_setprio 0
	s_add_i32 s50, s50, 2
	s_add_u32 s41, s41, 0x100
	s_addc_u32 s49, s49, 0
	s_add_u32 s92, s92, 0x100
	s_addc_u32 s93, s93, 0
	s_cmp_gt_u32 s50, 13
	s_cbranch_scc0 .LBB0_306
	v_readlane_b32 s4, v254, 46
	v_readlane_b32 s5, v254, 47
	s_and_b64 vcc, exec, s[4:5]
	s_cbranch_vccz .LBB0_309
	s_barrier
